# LDS-DMA staging version with unreachable padding so the later GEMM loops sit at the baseline code placement (mod 256)
# speedup vs baseline: 1.0046x; 1.0046x over previous
; __device__ __forceinline__ int crow(int r, int hi) { return (r & 3) + 8 * (r >> 2) + 4 * hi; }
; __device__ __forceinline__ void na_wave_units(int gw, int NGW, const bf16_t* QA, bf16_t* AB, const float* rpb  , ALAS char* lds) {
;     ...
;       if (__builtin_expect(!__all(pmax <= THR2), 0)) {
;         const float dl = fmaxf(pmax, 0.f); m_ref += dl;
; #pragma unroll
;         for (int q = 0; q < 16; ++q) { p0[q] -= dl; p1[q] -= dl; negm[q] = -m_ref; }
;         const float f = __builtin_amdgcn_exp2f(-dl);
; #pragma unroll
;         for (int q = 0; q < 16; ++q) { const float ar = __shfl(f, crow(q, hi), 64); osum[q] *= ar; o[0][q] *= ar; o[1][q] *= ar; }
;       }
.LBB0_839:
	v_max_f32_e32 v64, v64, v64
	v_max_f32_e32 v83, 0, v64
	v_exp_f32_e64 v97, -v83
	v_and_or_b32 v64, v234, 64, v193
	v_lshlrev_b32_e32 v96, 2, v64
	v_or_b32_e32 v98, 0x6c, v96
	ds_bpermute_b32 v64, v96, v97
	ds_bpermute_b32 v65, v96, v97 offset:4
	ds_bpermute_b32 v84, v96, v97 offset:8
	ds_bpermute_b32 v85, v96, v97 offset:12
	ds_bpermute_b32 v86, v96, v97 offset:32
	ds_bpermute_b32 v87, v96, v97 offset:36
	ds_bpermute_b32 v88, v96, v97 offset:40
	ds_bpermute_b32 v89, v96, v97 offset:44
	ds_bpermute_b32 v90, v96, v97 offset:64
	ds_bpermute_b32 v91, v96, v97 offset:68
	ds_bpermute_b32 v92, v96, v97 offset:96
	ds_bpermute_b32 v93, v96, v97 offset:100
	ds_bpermute_b32 v94, v96, v97 offset:72
	ds_bpermute_b32 v95, v96, v97 offset:76
	ds_bpermute_b32 v96, v96, v97 offset:104
	ds_bpermute_b32 v97, v98, v97
	s_waitcnt lgkmcnt(4)
	v_pk_mul_f32 v[30:31], v[30:31], v[92:93]
	v_pk_mul_f32 v[46:47], v[46:47], v[92:93]
	v_pk_mul_f32 v[14:15], v[14:15], v[92:93]
	s_waitcnt lgkmcnt(2)
	v_pk_mul_f32 v[28:29], v[28:29], v[94:95]
	v_pk_mul_f32 v[44:45], v[44:45], v[94:95]
	v_pk_mul_f32 v[12:13], v[12:13], v[94:95]
	v_pk_mul_f32 v[26:27], v[26:27], v[90:91]
	v_pk_mul_f32 v[42:43], v[42:43], v[90:91]
	v_pk_mul_f32 v[10:11], v[10:11], v[90:91]
	v_pk_mul_f32 v[24:25], v[24:25], v[88:89]
	v_pk_mul_f32 v[40:41], v[40:41], v[88:89]
	v_pk_mul_f32 v[8:9], v[8:9], v[88:89]
	v_pk_mul_f32 v[22:23], v[22:23], v[86:87]
	v_pk_mul_f32 v[38:39], v[38:39], v[86:87]
	v_pk_mul_f32 v[6:7], v[6:7], v[86:87]
	v_pk_mul_f32 v[20:21], v[20:21], v[84:85]
	v_pk_mul_f32 v[36:37], v[36:37], v[84:85]
	v_pk_mul_f32 v[4:5], v[4:5], v[84:85]
	v_pk_mul_f32 v[18:19], v[18:19], v[64:65]
	v_pk_mul_f32 v[34:35], v[34:35], v[64:65]
	v_pk_mul_f32 v[2:3], v[2:3], v[64:65]
	s_waitcnt lgkmcnt(0)
	v_pk_mul_f32 v[32:33], v[32:33], v[96:97]
	v_pk_mul_f32 v[48:49], v[48:49], v[96:97]
	v_pk_mul_f32 v[16:17], v[16:17], v[96:97]
	v_sub_f32_e32 v63, v63, v83
	v_sub_f32_e32 v62, v62, v83
	v_sub_f32_e32 v61, v61, v83
	v_sub_f32_e32 v60, v60, v83
	v_sub_f32_e32 v59, v59, v83
	v_sub_f32_e32 v58, v58, v83
	v_sub_f32_e32 v57, v57, v83
	v_sub_f32_e32 v56, v56, v83
	v_sub_f32_e32 v55, v55, v83
	v_sub_f32_e32 v54, v54, v83
	v_sub_f32_e32 v53, v53, v83
	v_sub_f32_e32 v52, v52, v83
	v_sub_f32_e32 v51, v51, v83
	v_sub_f32_e32 v50, v50, v83
	v_sub_f32_e32 v1, v1, v83
	v_sub_f32_e32 v66, v66, v83
	v_sub_f32_e32 v81, v81, v83
	v_sub_f32_e32 v82, v82, v83
	v_sub_f32_e32 v79, v79, v83
	v_sub_f32_e32 v80, v80, v83
	v_sub_f32_e32 v77, v77, v83
	v_sub_f32_e32 v78, v78, v83
	v_sub_f32_e32 v75, v75, v83
	v_sub_f32_e32 v76, v76, v83
	v_sub_f32_e32 v73, v73, v83
	v_sub_f32_e32 v74, v74, v83
	v_sub_f32_e32 v71, v71, v83
	v_sub_f32_e32 v72, v72, v83
	v_sub_f32_e32 v69, v69, v83
	v_sub_f32_e32 v70, v70, v83
	v_sub_f32_e32 v67, v67, v83
	v_sub_f32_e32 v68, v68, v83
	s_branch .LBB0_831
	s_nop 0
	s_nop 0
	s_nop 0
	s_nop 0
	s_nop 0
	s_nop 0
	s_nop 0
	s_nop 0
	s_nop 0
	s_nop 0
	s_nop 0
	s_nop 0
	s_nop 0
	s_nop 0
	s_nop 0
	s_nop 0
	s_nop 0
	s_nop 0
	s_nop 0
	s_nop 0
	s_nop 0
	s_nop 0
	s_nop 0
	s_nop 0
	s_nop 0
	s_nop 0
